# static priority raise for waves 0..3 in GEMM phases + packed f32 multiplies between the scan's MFMAs split into single ops
# speedup vs baseline: 1.0006x; 1.0006x over previous
; __device__ __forceinline__ void phase_scan(const Params& p, LAS unsigned char* lds, int bh, int wave_s) {
;     ...
;         for (int s = 0; s < 4; ++s) Sb[s] = acc2frag(Sacc[2 * s], Sacc[2 * s + 1]);
;         f32x4 vn[4], o[4];
;         bf16x8 wf[2][4], qf[2][4];
; #pragma unroll
;         for (int s = 0; s < 4; ++s) { wf[0][s] = ldfrag(img + IMG_WD + fr * SWD + 32 * s + 4 * fq); qf[0][s] = ldfrag(img + IMG_QD + fr * SWD + 32 * s + 4 * fq); }
; #pragma unroll
;         for (int mm = 0; mm < 4; ++mm) {
;             if (mm < 3) {
; #pragma unroll
;                 for (int s = 0; s < 4; ++s) { wf[(mm + 1) & 1][s] = ldfrag(img + IMG_WD + (16 * (mm + 1) + fr) * SWD + 32 * s + 4 * fq); qf[(mm + 1) & 1][s] = ldfrag(img + IMG_QD + (16 * (mm + 1) + fr) * SWD + 32 * s + 4 * fq); } }
;             f32x4 c = (f32x4){0.f, 0.f, 0.f, 0.f}, d = (f32x4){0.f, 0.f, 0.f, 0.f};
; #pragma unroll
;             for (int s = 0; s < 4; ++s) {
;                 c = __builtin_amdgcn_mfma_f32_16x16x32_bf16(wf[mm & 1][s], Sb[s], c, 0, 0, 0);
;                 d = __builtin_amdgcn_mfma_f32_16x16x32_bf16(qf[mm & 1][s], Sb[s], d, 0, 0, 0);
;             }
;             vn[mm] = ucur[mm] - c; o[mm] = d;
;         }
;         bf16x8 kq[4][2], kt[4][2];
; #pragma unroll
;         for (int mm = 0; mm < 4; ++mm)
; #pragma unroll
;             for (int s = 0; s < 2; ++s) kq[mm][s] = ldfrag(img + IMG_QK + (16 * mm + fr) * SKT + 32 * s + 4 * fq);
; #pragma unroll
;         for (int m = 0; m < 4; ++m)
; #pragma unroll
;             for (int s = 0; s < 2; ++s) kt[m][s] = ldfrag(img + IMG_KT + (16 * m + fr) * SKT + 32 * s + 4 * fq);
;         bf16x8 vb[2];
; #pragma unroll
;         for (int s = 0; s < 2; ++s) vb[s] = acc2frag(vn[2 * s], vn[2 * s + 1]);
; #pragma unroll
;         for (int mm = 0; mm < 4; ++mm)
; #pragma unroll
;             for (int s = 0; s < 2; ++s) o[mm] = __builtin_amdgcn_mfma_f32_16x16x32_bf16(kq[mm][s], vb[s], o[mm], 0, 0, 0);
; #pragma unroll
;         for (int m = 0; m < 4; ++m)
; #pragma unroll
;             for (int s = 0; s < 2; ++s) kq[m][s] = ldfrag(img + IMG_KT + (16 * (m + 4) + fr) * SKT + 32 * s + 4 * fq);
; #pragma unroll
;         for (int m = 0; m < 4; ++m) {
;             f32x4 c = Sacc[m] * glcur;
; #pragma unroll
;             for (int s = 0; s < 2; ++s) c = __builtin_amdgcn_mfma_f32_16x16x32_bf16(kt[m][s], vb[s], c, 0, 0, 0);
;             Sacc[m] = c;
.LBB0_934:
	s_mul_i32 s36, s57, 0xec00
	s_mov_b32 s57, s37
	s_lshl_b64 s[60:61], s[56:57], 15
	s_ashr_i32 s57, s56, 31
	s_lshl_b64 s[58:59], s[56:57], 2
	s_add_u32 s58, s25, s58
	s_addc_u32 s59, s62, s59
	s_add_i32 s36, s36, 0
	v_lshlrev_b32_e32 v107, 1, v87
	v_add3_u32 v116, s36, v76, v107
	ds_read2_b64 v[48:51], v116 offset1:4
	v_add_u32_e32 v120, 0x4000, v116
	ds_read2_b64 v[64:67], v116 offset0:8 offset1:12
	ds_read2_b64 v[60:63], v120 offset0:64 offset1:68
	v_cvt_pk_bf16_f32 v56, v28, v29
	v_cvt_pk_bf16_f32 v57, v30, v31
	v_cvt_pk_bf16_f32 v58, v24, v25
	v_cvt_pk_bf16_f32 v59, v26, v27
	ds_read2_b64 v[68:71], v120 offset0:72 offset1:76
	v_cvt_pk_bf16_f32 v52, v20, v21
	s_waitcnt lgkmcnt(0)
	v_mfma_f32_16x16x32_bf16 v[48:51], v[48:51], v[56:59], 0
	v_cvt_pk_bf16_f32 v53, v22, v23
	v_cvt_pk_bf16_f32 v54, v16, v17
	v_cvt_pk_bf16_f32 v55, v18, v19
	ds_read2_b64 v[112:115], v116 offset0:16 offset1:20
	v_mfma_f32_16x16x32_bf16 v[60:63], v[60:63], v[56:59], 0
	ds_read2_b64 v[116:119], v116 offset0:24 offset1:28
	v_cvt_pk_bf16_f32 v108, v12, v13
	v_cvt_pk_bf16_f32 v109, v14, v15
	v_mfma_f32_16x16x32_bf16 v[48:51], v[64:67], v[52:55], v[48:51]
	ds_read2_b64 v[64:67], v120 offset0:80 offset1:84
	v_cvt_pk_bf16_f32 v110, v8, v9
	v_cvt_pk_bf16_f32 v111, v10, v11
	v_mfma_f32_16x16x32_bf16 v[60:63], v[68:71], v[52:55], v[60:63]
	v_add3_u32 v107, s36, v107, v76
	v_cvt_pk_bf16_f32 v68, v4, v5
	v_cvt_pk_bf16_f32 v69, v6, v7
	s_waitcnt lgkmcnt(0)
	v_mfma_f32_16x16x32_bf16 v[48:51], v[112:115], v[108:111], v[48:51]
	v_cvt_pk_bf16_f32 v70, v0, v1
	v_cvt_pk_bf16_f32 v71, v2, v3
	v_add_u32_e32 v124, 0x1000, v107
	v_mfma_f32_16x16x32_bf16 v[60:63], v[64:67], v[108:111], v[60:63]
	s_mov_b32 m0, s86
	s_nop 0
	global_load_lds_dwordx4 v[204:205], off
	ds_read2_b64 v[64:67], v120 offset0:88 offset1:92
	v_add_u32_e32 v125, 0x5000, v107
	ds_read2_b64 v[120:123], v125 offset0:88 offset1:92
	v_mfma_f32_16x16x32_bf16 v[112:115], v[116:119], v[68:71], v[48:51]
	ds_read2_b64 v[116:119], v124 offset0:16 offset1:20
	v_add_u32_e32 v132, 0x2000, v107
	v_add_u32_e32 v133, 0x6000, v107
	s_waitcnt lgkmcnt(0)
	v_mfma_f32_16x16x32_bf16 v[48:51], v[64:67], v[68:71], v[60:63]
	ds_read2_b64 v[128:131], v133 offset0:104 offset1:108
	s_nop 1
	ds_read2_b64 v[60:63], v125 offset0:80 offset1:84
	v_add_u32_e32 v137, 0x3000, v107
	v_mfma_f32_16x16x32_bf16 v[64:67], v[116:119], v[56:59], 0
	ds_read2_b64 v[116:119], v124 offset0:24 offset1:28
	v_sub_f32_e32 v136, v35, v115
	v_sub_f32_e32 v138, v34, v114
	s_waitcnt lgkmcnt(0)
	v_mfma_f32_16x16x32_bf16 v[60:63], v[60:63], v[56:59], 0
	v_add_u32_e32 v107, 0x7000, v107
	v_mul_f32_e32 v30, v30, v84
	v_mul_f32_e32 v31, v31, v84
	v_mul_f32_e32 v28, v28, v84
	v_mul_f32_e32 v29, v29, v84
	v_mfma_f32_16x16x32_bf16 v[64:67], v[116:119], v[52:55], v[64:67]
	ds_read2_b64 v[116:119], v124 offset0:32 offset1:36
	v_mul_f32_e32 v26, v26, v84
	v_mul_f32_e32 v27, v27, v84
	v_mul_f32_e32 v24, v24, v84
	v_mul_f32_e32 v25, v25, v84
	v_mfma_f32_16x16x32_bf16 v[60:63], v[120:123], v[52:55], v[60:63]
	s_mov_b32 m0, s87
	s_nop 0
	global_load_lds_dwordx4 v[206:207], off
	ds_read2_b64 v[120:123], v125 offset0:96 offset1:100
	v_mul_f32_e32 v22, v22, v84
	v_mul_f32_e32 v23, v23, v84
	v_mul_f32_e32 v20, v20, v84
	v_mul_f32_e32 v21, v21, v84
	s_waitcnt lgkmcnt(0)
	v_mfma_f32_16x16x32_bf16 v[64:67], v[116:119], v[108:111], v[64:67]
	ds_read2_b64 v[116:119], v124 offset0:40 offset1:44
	v_mul_f32_e32 v18, v18, v84
	v_mul_f32_e32 v19, v19, v84
	v_mul_f32_e32 v16, v16, v84
	v_mul_f32_e32 v17, v17, v84
	v_mfma_f32_16x16x32_bf16 v[60:63], v[120:123], v[108:111], v[60:63]
	ds_read2_b64 v[120:123], v125 offset0:104 offset1:108
	ds_read2_b64 v[124:127], v132 offset0:40 offset1:44
	v_mul_f32_e32 v14, v14, v84
	v_mul_f32_e32 v15, v15, v84
	s_waitcnt lgkmcnt(0)
	v_mfma_f32_16x16x32_bf16 v[64:67], v[116:119], v[68:71], v[64:67]
	ds_read2_b64 v[116:119], v132 offset0:32 offset1:36
	v_mul_f32_e32 v12, v12, v84
	v_mul_f32_e32 v13, v13, v84
	v_mul_f32_e32 v10, v10, v84
	v_mul_f32_e32 v11, v11, v84
	v_mfma_f32_16x16x32_bf16 v[60:63], v[120:123], v[68:71], v[60:63]
	ds_read2_b64 v[120:123], v133 offset0:96 offset1:100
	s_nop 2
	v_sub_f32_e32 v139, v37, v65
	v_sub_f32_e32 v140, v36, v64
	s_waitcnt lgkmcnt(0)
; __device__ __forceinline__ void phase_scan(const Params& p, LAS unsigned char* lds, int bh, int wave_s) {
;     ...
;         for (int s = 0; s < 4; ++s) { wf[0][s] = ldfrag(img + IMG_WD + fr * SWD + 32 * s + 4 * fq); qf[0][s] = ldfrag(img + IMG_QD + fr * SWD + 32 * s + 4 * fq); }
; #pragma unroll
;         for (int mm = 0; mm < 4; ++mm) {
;             if (mm < 3) {
; #pragma unroll
;                 for (int s = 0; s < 4; ++s) { wf[(mm + 1) & 1][s] = ldfrag(img + IMG_WD + (16 * (mm + 1) + fr) * SWD + 32 * s + 4 * fq); qf[(mm + 1) & 1][s] = ldfrag(img + IMG_QD + (16 * (mm + 1) + fr) * SWD + 32 * s + 4 * fq); } }
;             f32x4 c = (f32x4){0.f, 0.f, 0.f, 0.f}, d = (f32x4){0.f, 0.f, 0.f, 0.f};
; #pragma unroll
;             for (int s = 0; s < 4; ++s) {
;                 c = __builtin_amdgcn_mfma_f32_16x16x32_bf16(wf[mm & 1][s], Sb[s], c, 0, 0, 0);
;                 d = __builtin_amdgcn_mfma_f32_16x16x32_bf16(qf[mm & 1][s], Sb[s], d, 0, 0, 0);
;             }
;             vn[mm] = ucur[mm] - c; o[mm] = d;
;         }
;         bf16x8 kq[4][2], kt[4][2];
; #pragma unroll
;         for (int mm = 0; mm < 4; ++mm)
; #pragma unroll
;             for (int s = 0; s < 2; ++s) kq[mm][s] = ldfrag(img + IMG_QK + (16 * mm + fr) * SKT + 32 * s + 4 * fq);
; #pragma unroll
;         for (int m = 0; m < 4; ++m)
; #pragma unroll
;             for (int s = 0; s < 2; ++s) kt[m][s] = ldfrag(img + IMG_KT + (16 * m + fr) * SKT + 32 * s + 4 * fq);
;         bf16x8 vb[2];
; #pragma unroll
;         for (int s = 0; s < 2; ++s) vb[s] = acc2frag(vn[2 * s], vn[2 * s + 1]);
; #pragma unroll
;         for (int mm = 0; mm < 4; ++mm)
; #pragma unroll
;             for (int s = 0; s < 2; ++s) o[mm] = __builtin_amdgcn_mfma_f32_16x16x32_bf16(kq[mm][s], vb[s], o[mm], 0, 0, 0);
; #pragma unroll
;         for (int m = 0; m < 4; ++m)
; #pragma unroll
;             for (int s = 0; s < 2; ++s) kq[m][s] = ldfrag(img + IMG_KT + (16 * (m + 4) + fr) * SKT + 32 * s + 4 * fq);
; #pragma unroll
;         for (int m = 0; m < 4; ++m) {
;             f32x4 c = Sacc[m] * glcur;
; #pragma unroll
;             for (int s = 0; s < 2; ++s) c = __builtin_amdgcn_mfma_f32_16x16x32_bf16(kt[m][s], vb[s], c, 0, 0, 0);
;             Sacc[m] = c;
;         }
; #pragma unroll
;         for (int m = 0; m < 4; ++m) {
;             f32x4 c = Sacc[m + 4] * glcur;
; #pragma unroll
	v_mfma_f32_16x16x32_bf16 v[116:119], v[116:119], v[56:59], 0
	v_mul_f32_e64 v8, v8, v84
	v_mul_f32_e64 v9, v9, v84
	v_mul_f32_e32 v6, v6, v84
	v_mul_f32_e32 v7, v7, v84
	v_mul_f32_e32 v4, v4, v84
	v_mul_f32_e32 v5, v5, v84
	v_mfma_f32_16x16x32_bf16 v[120:123], v[120:123], v[56:59], 0
	s_mov_b32 m0, s88
	s_nop 0
	global_load_lds_dwordx4 v[208:209], off
	v_mul_f32_e64 v2, v2, v84
	v_mul_f32_e64 v3, v3, v84
	v_mul_f32_e32 v0, v0, v84
	v_mul_f32_e32 v1, v1, v84
	v_mfma_f32_16x16x32_bf16 v[116:119], v[124:127], v[52:55], v[116:119]
	ds_read2_b64 v[124:127], v132 offset0:48 offset1:52
	v_mfma_f32_16x16x32_bf16 v[120:123], v[128:131], v[52:55], v[120:123]
	ds_read2_b64 v[128:131], v133 offset0:112 offset1:116
	s_waitcnt lgkmcnt(0)
	v_mfma_f32_16x16x32_bf16 v[116:119], v[124:127], v[108:111], v[116:119]
	ds_read2_b64 v[124:127], v132 offset0:56 offset1:60
	ds_read2_b64 v[132:135], v133 offset0:120 offset1:124
	v_mfma_f32_16x16x32_bf16 v[120:123], v[128:131], v[108:111], v[120:123]
	ds_read2_b64 v[128:131], v137 offset0:48 offset1:52
	s_waitcnt lgkmcnt(0)
	v_mfma_f32_16x16x32_bf16 v[120:123], v[132:135], v[68:71], v[120:123]
	v_sub_f32_e32 v132, v33, v113
	v_sub_f32_e32 v133, v32, v112
	ds_read2_b64 v[32:35], v137 offset0:56 offset1:60
	v_mfma_f32_16x16x32_bf16 v[112:115], v[128:131], v[56:59], 0
	s_mov_b32 m0, s89
	s_nop 0
	global_load_lds_dwordx4 v[210:211], off
	ds_read2_b64 v[128:131], v137 offset0:64 offset1:68
	v_sub_f32_e32 v134, v39, v67
	v_sub_f32_e32 v135, v38, v66
	v_mfma_f32_16x16x32_bf16 v[116:119], v[124:127], v[68:71], v[116:119]
	ds_read2_b64 v[124:127], v107 offset0:112 offset1:116
	ds_read2_b64 v[36:39], v137 offset0:72 offset1:76
	s_waitcnt lgkmcnt(0)
	v_mfma_f32_16x16x32_bf16 v[32:35], v[32:35], v[52:55], v[112:115]
	v_mfma_f32_16x16x32_bf16 v[32:35], v[128:131], v[108:111], v[32:35]
	v_add3_u32 v130, s36, v89, v96
	s_nop 1
	v_sub_f32_e32 v116, v40, v116
	v_add_u32_e32 v40, 0xc800, v130
	v_mfma_f32_16x16x32_bf16 v[56:59], v[124:127], v[56:59], 0
	ds_read2_b64 v[64:67], v107 offset0:120 offset1:124
	ds_read2_b64 v[112:115], v107 offset0:128 offset1:132
	ds_read2_b64 v[124:127], v107 offset0:136 offset1:140
	v_sub_f32_e32 v107, v43, v119
	v_sub_f32_e32 v118, v42, v118
	v_mfma_f32_16x16x32_bf16 v[32:35], v[36:39], v[68:71], v[32:35]
	v_sub_f32_e32 v117, v41, v117
	v_add_u32_e32 v131, 0x8000, v130
	s_nop 5
	v_sub_f32_e32 v119, v47, v35
	v_sub_f32_e32 v128, v46, v34
	s_waitcnt lgkmcnt(0)
	v_mfma_f32_16x16x32_bf16 v[34:37], v[64:67], v[52:55], v[56:59]
	s_mov_b32 m0, s90
	s_nop 0
	global_load_lds_dwordx4 v[212:213], off
	v_sub_f32_e32 v52, v45, v33
	v_sub_f32_e32 v53, v44, v32
	v_add_u32_e32 v54, 0xd000, v130
	v_mfma_f32_16x16x32_bf16 v[32:35], v[112:115], v[108:111], v[34:37]
	s_nop 3
	ds_read2_b64 v[36:39], v40 offset1:4
	ds_read2_b64 v[40:43], v40 offset0:8 offset1:12
	v_cvt_pk_bf16_f32 v108, v133, v132
	v_cvt_pk_bf16_f32 v109, v138, v136
	v_cvt_pk_bf16_f32 v110, v140, v139
	v_cvt_pk_bf16_f32 v111, v135, v134
	v_mfma_f32_16x16x32_bf16 v[44:47], v[124:127], v[68:71], v[32:35]
	v_cvt_pk_bf16_f32 v112, v116, v117
	v_cvt_pk_bf16_f32 v113, v118, v107
	v_cvt_pk_bf16_f32 v114, v53, v52
	ds_read2_b64 v[32:35], v54 offset0:16 offset1:20
	s_waitcnt lgkmcnt(0)
	v_mfma_f32_16x16x32_bf16 v[36:39], v[36:39], v[108:111], v[48:51]
	v_cvt_pk_bf16_f32 v115, v128, v119
	v_lshl_add_u64 v[128:129], v[80:81], 0, s[60:61]
	s_nop 0
	v_mfma_f32_16x16x32_bf16 v[68:71], v[40:43], v[112:115], v[36:39]
	v_add_u32_e32 v48, 0xd800, v130
	ds_read2_b64 v[40:43], v48 offset0:32 offset1:36
	ds_read2_b64 v[56:59], v48 offset0:40 offset1:44
	s_nop 0
	ds_read2_b64 v[36:39], v54 offset0:24 offset1:28
	v_mfma_f32_16x16x32_bf16 v[32:35], v[32:35], v[108:111], v[60:63]
	s_nop 1
	s_nop 0
	s_waitcnt lgkmcnt(0)
	v_mfma_f32_16x16x32_bf16 v[64:67], v[36:39], v[112:115], v[32:35]
	s_cmp_lt_u32 s4, 0xc00
	s_cbranch_scc0 .Lscan_dma7_skip
	s_mov_b32 m0, s91
	s_nop 0
	global_load_lds_dwordx4 v[214:215], off
